# attention hot path: rescale decision after MFMA 20
# baseline (speedup 1.0000x reference)
.Latt_prio_skip:
	v_xor_b32_e32 v84, 0x80000000, v239
	v_mov_b32_e32 v85, v84
	v_mov_b32_e32 v86, v84
	v_mov_b32_e32 v87, v84
	v_mov_b32_e32 v88, v84
	v_mov_b32_e32 v89, v84
	v_mov_b32_e32 v90, v84
	v_mov_b32_e32 v91, v84
	v_mov_b32_e32 v92, v84
	v_mov_b32_e32 v93, v84
	v_mov_b32_e32 v94, v84
	v_mov_b32_e32 v95, v84
	v_mov_b32_e32 v96, v84
	v_mov_b32_e32 v97, v84
	v_mov_b32_e32 v98, v84
	v_mov_b32_e32 v99, v84
	s_waitcnt lgkmcnt(5)
	s_nop 0
	v_mfma_f32_32x32x16_bf16 v[36:51], v[100:103], v[132:135], v[84:99]
	ds_read_b128 v[100:103], v124 offset:6656
	s_waitcnt lgkmcnt(5)
	v_mfma_f32_32x32x16_bf16 v[36:51], v[104:107], v[136:139], v[36:51]
	ds_read_b128 v[104:107], v124 offset:6688
	s_waitcnt lgkmcnt(5)
	v_mfma_f32_32x32x16_bf16 v[36:51], v[108:111], v[140:143], v[36:51]
	ds_read_b128 v[108:111], v124 offset:6720
	s_waitcnt lgkmcnt(5)
	v_mfma_f32_32x32x16_bf16 v[36:51], v[112:115], v[144:147], v[36:51]
	ds_read_b128 v[112:115], v124 offset:6752
	s_waitcnt lgkmcnt(5)
	v_mfma_f32_32x32x16_bf16 v[36:51], v[116:119], v[148:151], v[36:51]
	ds_read_b128 v[116:119], v124 offset:6784
	s_waitcnt lgkmcnt(5)
	v_mfma_f32_32x32x16_bf16 v[36:51], v[120:123], v[152:155], v[36:51]
	ds_read_b128 v[120:123], v124 offset:6816
	s_waitcnt lgkmcnt(5)
	v_mfma_f32_32x32x16_bf16 v[52:67], v[100:103], v[132:135], v[84:99]
	ds_read_b128 v[100:103], v124 offset:13312
	s_waitcnt lgkmcnt(5)
	v_mfma_f32_32x32x16_bf16 v[52:67], v[104:107], v[136:139], v[52:67]
	ds_read_b128 v[104:107], v124 offset:13344
	s_waitcnt lgkmcnt(5)
	v_mfma_f32_32x32x16_bf16 v[52:67], v[108:111], v[140:143], v[52:67]
	ds_read_b128 v[108:111], v124 offset:13376
	s_waitcnt lgkmcnt(5)
	v_mfma_f32_32x32x16_bf16 v[52:67], v[112:115], v[144:147], v[52:67]
	ds_read_b128 v[112:115], v124 offset:13408
	s_waitcnt lgkmcnt(5)
	v_mfma_f32_32x32x16_bf16 v[52:67], v[116:119], v[148:151], v[52:67]
	ds_read_b128 v[116:119], v124 offset:13440
	s_waitcnt lgkmcnt(5)
	v_mfma_f32_32x32x16_bf16 v[52:67], v[120:123], v[152:155], v[52:67]
	ds_read_b128 v[120:123], v124 offset:13472
	s_waitcnt lgkmcnt(5)
	v_mfma_f32_32x32x16_bf16 v[68:83], v[100:103], v[132:135], v[84:99]
	ds_read_b128 v[100:103], v124 offset:19968
	v_max3_f32 v125, v36, v37, v38
	v_max3_f32 v125, v125, v39, v40
	v_max3_f32 v125, v125, v41, v42
	s_waitcnt lgkmcnt(5)
	v_mfma_f32_32x32x16_bf16 v[68:83], v[104:107], v[136:139], v[68:83]
	ds_read_b128 v[104:107], v124 offset:20000
	v_max3_f32 v125, v125, v43, v44
	v_max3_f32 v125, v125, v45, v46
	v_max3_f32 v125, v125, v47, v48
	s_waitcnt lgkmcnt(5)
	v_mfma_f32_32x32x16_bf16 v[68:83], v[108:111], v[140:143], v[68:83]
	ds_read_b128 v[108:111], v124 offset:20032
	v_max3_f32 v125, v125, v49, v50
	v_max3_f32 v129, v51, v52, v53
	v_max3_f32 v129, v129, v54, v55
	s_waitcnt lgkmcnt(5)
	v_mfma_f32_32x32x16_bf16 v[68:83], v[112:115], v[144:147], v[68:83]
	ds_read_b128 v[112:115], v124 offset:20064
	v_max3_f32 v129, v129, v56, v57
	v_max3_f32 v129, v129, v58, v59
	v_max3_f32 v129, v129, v60, v61
	s_waitcnt lgkmcnt(5)
	v_mfma_f32_32x32x16_bf16 v[68:83], v[116:119], v[148:151], v[68:83]
	ds_read_b128 v[116:119], v124 offset:20096
	v_max3_f32 v129, v129, v62, v63
	v_max3_f32 v129, v129, v64, v65
	v_max3_f32 v129, v129, v66, v67
	s_waitcnt lgkmcnt(5)
	v_mfma_f32_32x32x16_bf16 v[68:83], v[120:123], v[152:155], v[68:83]
	ds_read_b128 v[120:123], v124 offset:20128
	v_max_f32_e32 v125, v125, v129
	v_mov_b32_e32 v126, v125
	s_nop 1
	v_permlane32_swap_b32_e32 v125, v126
	s_waitcnt lgkmcnt(5)
	v_mfma_f32_32x32x16_bf16 v[84:99], v[100:103], v[132:135], v[84:99]
	ds_read_b128 v[100:103], v185 offset:26624
	v_max_f32_e32 v125, v125, v126
	s_waitcnt lgkmcnt(5)
	v_mfma_f32_32x32x16_bf16 v[84:99], v[104:107], v[136:139], v[84:99]
	ds_read_b128 v[104:107], v185 offset:35328
	s_cmp_eq_u32 s86, 0
	s_cbranch_scc1 .Latt_slow0
	v_cmp_lt_f32_e32 vcc, s95, v125
	s_cbranch_vccnz .Latt_slow0
	s_waitcnt lgkmcnt(5)
	v_mfma_f32_32x32x16_bf16 v[84:99], v[108:111], v[140:143], v[84:99]
	ds_read_b128 v[108:111], v185 offset:26656
	v_exp_f32_e32 v36, v36
	v_exp_f32_e32 v37, v37
	v_exp_f32_e32 v38, v38
	v_exp_f32_e32 v39, v39
	v_exp_f32_e32 v40, v40
	v_exp_f32_e32 v41, v41
	v_exp_f32_e32 v42, v42
	v_exp_f32_e32 v43, v43
	v_add_f32_e32 v127, v36, v37
	v_add_f32_e32 v127, v38, v127
	v_add_f32_e32 v127, v39, v127
	v_add_f32_e32 v127, v40, v127
	v_add_f32_e32 v127, v41, v127
	v_add_f32_e32 v127, v42, v127
	v_add_f32_e32 v127, v43, v127
	v_cvt_pk_bf16_f32 v36, v36, v37
	v_cvt_pk_bf16_f32 v37, v38, v39
	v_cvt_pk_bf16_f32 v38, v40, v41
	v_cvt_pk_bf16_f32 v39, v42, v43
	v_exp_f32_e32 v44, v44
	s_waitcnt lgkmcnt(5)
	v_mfma_f32_32x32x16_bf16 v[84:99], v[112:115], v[144:147], v[84:99]
	ds_read_b128 v[112:115], v185 offset:35360
	v_exp_f32_e32 v45, v45
	v_exp_f32_e32 v46, v46
	v_exp_f32_e32 v47, v47
	v_exp_f32_e32 v48, v48
	v_exp_f32_e32 v49, v49
	v_exp_f32_e32 v50, v50
	v_exp_f32_e32 v51, v51
	v_add_f32_e32 v127, v44, v127
	v_add_f32_e32 v127, v45, v127
	v_add_f32_e32 v127, v46, v127
	v_add_f32_e32 v127, v47, v127
	v_add_f32_e32 v127, v48, v127
	v_add_f32_e32 v127, v49, v127
	v_add_f32_e32 v127, v50, v127
	v_add_f32_e32 v127, v51, v127
	v_cvt_pk_bf16_f32 v40, v44, v45
	v_cvt_pk_bf16_f32 v41, v46, v47
	v_cvt_pk_bf16_f32 v42, v48, v49
	v_cvt_pk_bf16_f32 v43, v50, v51
	v_exp_f32_e32 v52, v52
	s_waitcnt lgkmcnt(5)
	v_mfma_f32_32x32x16_bf16 v[84:99], v[116:119], v[148:151], v[84:99]
	ds_read_b128 v[116:119], v185 offset:26688
	v_exp_f32_e32 v53, v53
	v_exp_f32_e32 v54, v54
	v_exp_f32_e32 v55, v55
	v_exp_f32_e32 v56, v56
	v_exp_f32_e32 v57, v57
	v_exp_f32_e32 v58, v58
	v_exp_f32_e32 v59, v59
	v_add_f32_e32 v128, v52, v53
	v_add_f32_e32 v128, v54, v128
	v_add_f32_e32 v128, v55, v128
	v_add_f32_e32 v128, v56, v128
	v_add_f32_e32 v128, v57, v128
	v_add_f32_e32 v128, v58, v128
	v_add_f32_e32 v128, v59, v128
	v_cvt_pk_bf16_f32 v52, v52, v53
	v_cvt_pk_bf16_f32 v53, v54, v55
	v_cvt_pk_bf16_f32 v54, v56, v57
	v_cvt_pk_bf16_f32 v55, v58, v59
	v_exp_f32_e32 v60, v60
	v_exp_f32_e32 v61, v61
	s_waitcnt lgkmcnt(5)
	v_mfma_f32_32x32x16_bf16 v[84:99], v[120:123], v[152:155], v[84:99]
	ds_read_b128 v[120:123], v185 offset:35392
	v_exp_f32_e32 v62, v62
	v_exp_f32_e32 v63, v63
	v_exp_f32_e32 v64, v64
	v_exp_f32_e32 v65, v65
	v_exp_f32_e32 v66, v66
	v_exp_f32_e32 v67, v67
	v_add_f32_e32 v128, v60, v128
	v_add_f32_e32 v128, v61, v128
	v_add_f32_e32 v128, v62, v128
	v_add_f32_e32 v128, v63, v128
	v_add_f32_e32 v128, v64, v128
	v_add_f32_e32 v128, v65, v128
	v_add_f32_e32 v128, v66, v128
	v_add_f32_e32 v128, v67, v128
	v_cvt_pk_bf16_f32 v56, v60, v61
	v_cvt_pk_bf16_f32 v57, v62, v63
	v_cvt_pk_bf16_f32 v58, v64, v65
	v_cvt_pk_bf16_f32 v59, v66, v67
	v_add_f32_e32 v127, v127, v128
	v_add_f32_e32 v238, v238, v127
	s_waitcnt lgkmcnt(5)
	v_mfma_f32_32x32x16_bf16 v[4:19], v[100:103], v[36:39], v[4:19]
	ds_read_b128 v[100:103], v185 offset:26720
	v_max3_f32 v125, v68, v69, v70
	v_max3_f32 v125, v125, v71, v72
	v_max3_f32 v125, v125, v73, v74
	v_max3_f32 v125, v125, v75, v76
	v_max3_f32 v125, v125, v77, v78
	v_max3_f32 v125, v125, v79, v80
	v_max3_f32 v125, v125, v81, v82
	s_waitcnt lgkmcnt(5)
	v_mfma_f32_32x32x16_bf16 v[20:35], v[104:107], v[36:39], v[20:35]
	ds_read_b128 v[104:107], v185 offset:35424
	v_max3_f32 v129, v83, v84, v85
	v_max3_f32 v129, v129, v86, v87
	v_max3_f32 v129, v129, v88, v89
	v_max3_f32 v129, v129, v90, v91
	v_max3_f32 v129, v129, v92, v93
	v_max3_f32 v129, v129, v94, v95
	v_max3_f32 v129, v129, v96, v97
	s_waitcnt lgkmcnt(5)
	v_mfma_f32_32x32x16_bf16 v[4:19], v[108:111], v[40:43], v[4:19]
	ds_read_b128 v[108:111], v185 offset:26752
	v_max3_f32 v129, v129, v98, v99
	v_max_f32_e32 v125, v125, v129
	v_mov_b32_e32 v126, v125
	s_nop 1
	v_permlane32_swap_b32_e32 v125, v126
	v_max_f32_e32 v125, v125, v126
	v_cmp_lt_f32_e32 vcc, s95, v125
	s_cbranch_vccnz .Latt_slow1
	s_waitcnt lgkmcnt(5)
	v_mfma_f32_32x32x16_bf16 v[20:35], v[112:115], v[40:43], v[20:35]
	ds_read_b128 v[112:115], v185 offset:35456
	v_exp_f32_e32 v68, v68
	v_exp_f32_e32 v69, v69
	v_exp_f32_e32 v70, v70
	v_exp_f32_e32 v71, v71
	v_exp_f32_e32 v72, v72
	v_exp_f32_e32 v73, v73
	v_exp_f32_e32 v74, v74
	v_exp_f32_e32 v75, v75
	v_add_f32_e32 v127, v68, v69
	v_add_f32_e32 v127, v70, v127
	v_add_f32_e32 v127, v71, v127
	v_add_f32_e32 v127, v72, v127
	v_add_f32_e32 v127, v73, v127
	v_add_f32_e32 v127, v74, v127
	v_add_f32_e32 v127, v75, v127
	v_cvt_pk_bf16_f32 v68, v68, v69
	s_waitcnt lgkmcnt(5)
	v_mfma_f32_32x32x16_bf16 v[4:19], v[116:119], v[52:55], v[4:19]
	ds_read_b128 v[116:119], v185 offset:26784
	v_cvt_pk_bf16_f32 v69, v70, v71
	v_cvt_pk_bf16_f32 v70, v72, v73
	v_cvt_pk_bf16_f32 v71, v74, v75
	v_exp_f32_e32 v76, v76
	v_exp_f32_e32 v77, v77
	v_exp_f32_e32 v78, v78
	v_exp_f32_e32 v79, v79
	v_exp_f32_e32 v80, v80
	v_exp_f32_e32 v81, v81
	v_exp_f32_e32 v82, v82
	v_exp_f32_e32 v83, v83
	v_add_f32_e32 v127, v76, v127
	v_add_f32_e32 v127, v77, v127
	v_add_f32_e32 v127, v78, v127
	v_add_f32_e32 v127, v79, v127
	v_add_f32_e32 v127, v80, v127
	s_waitcnt lgkmcnt(5)
	v_mfma_f32_32x32x16_bf16 v[20:35], v[120:123], v[52:55], v[20:35]
	ds_read_b128 v[120:123], v185 offset:35488
	v_add_f32_e32 v127, v81, v127
	v_add_f32_e32 v127, v82, v127
	v_add_f32_e32 v127, v83, v127
	v_cvt_pk_bf16_f32 v72, v76, v77
	v_cvt_pk_bf16_f32 v73, v78, v79
	v_cvt_pk_bf16_f32 v74, v80, v81
	v_cvt_pk_bf16_f32 v75, v82, v83
	v_exp_f32_e32 v84, v84
	v_exp_f32_e32 v85, v85
	v_exp_f32_e32 v86, v86
	v_exp_f32_e32 v87, v87
	v_exp_f32_e32 v88, v88
	v_exp_f32_e32 v89, v89
	v_exp_f32_e32 v90, v90
	v_exp_f32_e32 v91, v91
	v_add_f32_e32 v128, v84, v85
	s_waitcnt lgkmcnt(5)
	v_mfma_f32_32x32x16_bf16 v[4:19], v[100:103], v[56:59], v[4:19]
	ds_read_b128 v[100:103], v185 offset:26816
	v_add_f32_e32 v128, v86, v128
	v_add_f32_e32 v128, v87, v128
	v_add_f32_e32 v128, v88, v128
	v_add_f32_e32 v128, v89, v128
	v_add_f32_e32 v128, v90, v128
	v_add_f32_e32 v128, v91, v128
	v_cvt_pk_bf16_f32 v84, v84, v85
	v_cvt_pk_bf16_f32 v85, v86, v87
	v_cvt_pk_bf16_f32 v86, v88, v89
	v_cvt_pk_bf16_f32 v87, v90, v91
	v_exp_f32_e32 v92, v92
	v_exp_f32_e32 v93, v93
	v_exp_f32_e32 v94, v94
	v_exp_f32_e32 v95, v95
	v_exp_f32_e32 v96, v96
	v_exp_f32_e32 v97, v97
	s_waitcnt lgkmcnt(5)
	v_mfma_f32_32x32x16_bf16 v[20:35], v[104:107], v[56:59], v[20:35]
	ds_read_b128 v[104:107], v185 offset:35520
	v_exp_f32_e32 v98, v98
	v_exp_f32_e32 v99, v99
	v_add_f32_e32 v128, v92, v128
	v_add_f32_e32 v128, v93, v128
	v_add_f32_e32 v128, v94, v128
	v_add_f32_e32 v128, v95, v128
	v_add_f32_e32 v128, v96, v128
	v_add_f32_e32 v128, v97, v128
	v_add_f32_e32 v128, v98, v128
	v_add_f32_e32 v128, v99, v128
	v_cvt_pk_bf16_f32 v88, v92, v93
	v_cvt_pk_bf16_f32 v89, v94, v95
	v_cvt_pk_bf16_f32 v90, v96, v97
	v_cvt_pk_bf16_f32 v91, v98, v99
	v_add_f32_e32 v127, v127, v128
	v_add_f32_e32 v238, v238, v127
	s_waitcnt lgkmcnt(5)
	v_mfma_f32_32x32x16_bf16 v[4:19], v[108:111], v[68:71], v[4:19]
	ds_read_b128 v[108:111], v185 offset:26848
	s_waitcnt lgkmcnt(5)
	v_mfma_f32_32x32x16_bf16 v[20:35], v[112:115], v[68:71], v[20:35]
	ds_read_b128 v[112:115], v185 offset:35552
	s_waitcnt lgkmcnt(5)
	v_mfma_f32_32x32x16_bf16 v[4:19], v[116:119], v[72:75], v[4:19]
	s_waitcnt lgkmcnt(4)
	v_mfma_f32_32x32x16_bf16 v[20:35], v[120:123], v[72:75], v[20:35]
	s_waitcnt lgkmcnt(3)
	v_mfma_f32_32x32x16_bf16 v[4:19], v[100:103], v[84:87], v[4:19]
	s_waitcnt lgkmcnt(2)
	v_mfma_f32_32x32x16_bf16 v[20:35], v[104:107], v[84:87], v[20:35]
	s_waitcnt lgkmcnt(1)
	v_mfma_f32_32x32x16_bf16 v[4:19], v[108:111], v[88:91], v[4:19]
	s_waitcnt lgkmcnt(0)
	v_mfma_f32_32x32x16_bf16 v[20:35], v[112:115], v[88:91], v[20:35]
	s_setprio 0
	s_branch .LBB0_631
.Latt_slow0:
	s_waitcnt lgkmcnt(5)
	v_mfma_f32_32x32x16_bf16 v[84:99], v[108:111], v[140:143], v[84:99]
	ds_read_b128 v[108:111], v185 offset:26656
	s_waitcnt lgkmcnt(5)
	v_mfma_f32_32x32x16_bf16 v[84:99], v[112:115], v[144:147], v[84:99]
	ds_read_b128 v[112:115], v185 offset:35360
	s_waitcnt lgkmcnt(5)
	v_mfma_f32_32x32x16_bf16 v[84:99], v[116:119], v[148:151], v[84:99]
	ds_read_b128 v[116:119], v185 offset:26688
	s_waitcnt lgkmcnt(5)
	v_mfma_f32_32x32x16_bf16 v[84:99], v[120:123], v[152:155], v[84:99]
	ds_read_b128 v[120:123], v185 offset:35392
	v_max_f32_e32 v130, 0, v125
	s_cmp_eq_u32 s86, 0
	s_cselect_b64 s[78:79], -1, 0
	v_cndmask_b32_e64 v130, v130, v125, s[78:79]
	v_exp_f32_e64 v131, -v130
	v_mov_b32_e32 v187, v130
	v_add_f32_e32 v239, v239, v130
	v_cndmask_b32_e64 v131, v131, 0, s[78:79]
	v_sub_f32_e32 v36, v36, v187
	v_sub_f32_e32 v37, v37, v187
	v_sub_f32_e32 v38, v38, v187
	v_sub_f32_e32 v39, v39, v187
	v_sub_f32_e32 v40, v40, v187
	v_sub_f32_e32 v41, v41, v187
	v_sub_f32_e32 v42, v42, v187
	v_sub_f32_e32 v43, v43, v187
	v_sub_f32_e32 v44, v44, v187
	v_sub_f32_e32 v45, v45, v187
	v_sub_f32_e32 v46, v46, v187
	v_sub_f32_e32 v47, v47, v187
	v_sub_f32_e32 v48, v48, v187
	v_sub_f32_e32 v49, v49, v187
	v_sub_f32_e32 v50, v50, v187
	v_sub_f32_e32 v51, v51, v187
	v_sub_f32_e32 v52, v52, v187
	v_sub_f32_e32 v53, v53, v187
	v_sub_f32_e32 v54, v54, v187
	v_sub_f32_e32 v55, v55, v187
	v_sub_f32_e32 v56, v56, v187
	v_sub_f32_e32 v57, v57, v187
	v_sub_f32_e32 v58, v58, v187
	v_sub_f32_e32 v59, v59, v187
	v_sub_f32_e32 v60, v60, v187
	v_sub_f32_e32 v61, v61, v187
	v_sub_f32_e32 v62, v62, v187
	v_sub_f32_e32 v63, v63, v187
	v_sub_f32_e32 v64, v64, v187
	v_sub_f32_e32 v65, v65, v187
	v_sub_f32_e32 v66, v66, v187
	v_sub_f32_e32 v67, v67, v187
	v_exp_f32_e32 v36, v36
	v_exp_f32_e32 v37, v37
	v_exp_f32_e32 v38, v38
	v_exp_f32_e32 v39, v39
	v_exp_f32_e32 v40, v40
	v_exp_f32_e32 v41, v41
	v_exp_f32_e32 v42, v42
	v_exp_f32_e32 v43, v43
	v_exp_f32_e32 v44, v44
	v_exp_f32_e32 v45, v45
	v_exp_f32_e32 v46, v46
	v_exp_f32_e32 v47, v47
	v_exp_f32_e32 v48, v48
	v_exp_f32_e32 v49, v49
	v_exp_f32_e32 v50, v50
	v_exp_f32_e32 v51, v51
	v_exp_f32_e32 v52, v52
	v_exp_f32_e32 v53, v53
	v_exp_f32_e32 v54, v54
	v_exp_f32_e32 v55, v55
	v_exp_f32_e32 v56, v56
	v_exp_f32_e32 v57, v57
	v_exp_f32_e32 v58, v58
	v_exp_f32_e32 v59, v59
	v_exp_f32_e32 v60, v60
	v_exp_f32_e32 v61, v61
	v_exp_f32_e32 v62, v62
	v_exp_f32_e32 v63, v63
	v_exp_f32_e32 v64, v64
	v_exp_f32_e32 v65, v65
	v_exp_f32_e32 v66, v66
	v_exp_f32_e32 v67, v67
	v_add_f32_e32 v127, v36, v37
	v_add_f32_e32 v127, v38, v127
	v_add_f32_e32 v127, v39, v127
	v_add_f32_e32 v127, v40, v127
	v_add_f32_e32 v127, v41, v127
	v_add_f32_e32 v127, v42, v127
	v_add_f32_e32 v127, v43, v127
	v_add_f32_e32 v127, v44, v127
	v_add_f32_e32 v127, v45, v127
	v_add_f32_e32 v127, v46, v127
	v_add_f32_e32 v127, v47, v127
	v_add_f32_e32 v127, v48, v127
	v_add_f32_e32 v127, v49, v127
	v_add_f32_e32 v127, v50, v127
	v_add_f32_e32 v127, v51, v127
	v_add_f32_e32 v127, v52, v127
	v_add_f32_e32 v127, v53, v127
	v_add_f32_e32 v127, v54, v127
	v_add_f32_e32 v127, v55, v127
	v_add_f32_e32 v127, v56, v127
	v_add_f32_e32 v127, v57, v127
	v_add_f32_e32 v127, v58, v127
	v_add_f32_e32 v127, v59, v127
	v_add_f32_e32 v127, v60, v127
	v_add_f32_e32 v127, v61, v127
	v_add_f32_e32 v127, v62, v127
	v_add_f32_e32 v127, v63, v127
	v_add_f32_e32 v127, v64, v127
	v_add_f32_e32 v127, v65, v127
	v_add_f32_e32 v127, v66, v127
	v_add_f32_e32 v127, v67, v127
	v_mul_f32_e32 v238, v238, v131
	v_add_f32_e32 v238, v238, v127
	v_mul_f32_e32 v4, v4, v131
	v_mul_f32_e32 v5, v5, v131
	v_mul_f32_e32 v6, v6, v131
	v_mul_f32_e32 v7, v7, v131
	v_mul_f32_e32 v8, v8, v131
	v_mul_f32_e32 v9, v9, v131
	v_mul_f32_e32 v10, v10, v131
	v_mul_f32_e32 v11, v11, v131
	v_mul_f32_e32 v12, v12, v131
	v_mul_f32_e32 v13, v13, v131
	v_mul_f32_e32 v14, v14, v131
	v_mul_f32_e32 v15, v15, v131
	v_mul_f32_e32 v16, v16, v131
	v_mul_f32_e32 v17, v17, v131
	v_mul_f32_e32 v18, v18, v131
	v_mul_f32_e32 v19, v19, v131
	v_mul_f32_e32 v20, v20, v131
	v_mul_f32_e32 v21, v21, v131
	v_mul_f32_e32 v22, v22, v131
	v_mul_f32_e32 v23, v23, v131
	v_mul_f32_e32 v24, v24, v131
	v_mul_f32_e32 v25, v25, v131
	v_mul_f32_e32 v26, v26, v131
	v_mul_f32_e32 v27, v27, v131
	v_mul_f32_e32 v28, v28, v131
	v_mul_f32_e32 v29, v29, v131
	v_mul_f32_e32 v30, v30, v131
	v_mul_f32_e32 v31, v31, v131
	v_mul_f32_e32 v32, v32, v131
	v_mul_f32_e32 v33, v33, v131
	v_mul_f32_e32 v34, v34, v131
	v_mul_f32_e32 v35, v35, v131
	v_mov_b32_e32 v242, v130
	v_cvt_pk_bf16_f32 v36, v36, v37
	v_cvt_pk_bf16_f32 v37, v38, v39
	v_cvt_pk_bf16_f32 v38, v40, v41
	v_cvt_pk_bf16_f32 v39, v42, v43
	v_cvt_pk_bf16_f32 v40, v44, v45
	v_cvt_pk_bf16_f32 v41, v46, v47
	v_cvt_pk_bf16_f32 v42, v48, v49
	v_cvt_pk_bf16_f32 v43, v50, v51
	v_cvt_pk_bf16_f32 v52, v52, v53
	v_cvt_pk_bf16_f32 v53, v54, v55
	v_cvt_pk_bf16_f32 v54, v56, v57
	v_cvt_pk_bf16_f32 v55, v58, v59
	v_cvt_pk_bf16_f32 v56, v60, v61
	v_cvt_pk_bf16_f32 v57, v62, v63
	v_cvt_pk_bf16_f32 v58, v64, v65
	v_cvt_pk_bf16_f32 v59, v66, v67
	s_waitcnt lgkmcnt(5)
	v_mfma_f32_32x32x16_bf16 v[4:19], v[100:103], v[36:39], v[4:19]
	ds_read_b128 v[100:103], v185 offset:26720
	s_waitcnt lgkmcnt(5)
	v_mfma_f32_32x32x16_bf16 v[20:35], v[104:107], v[36:39], v[20:35]
	ds_read_b128 v[104:107], v185 offset:35424
	s_waitcnt lgkmcnt(5)
	v_mfma_f32_32x32x16_bf16 v[4:19], v[108:111], v[40:43], v[4:19]
	ds_read_b128 v[108:111], v185 offset:26752
	s_branch .Latt_slowb
